# attention dense loops regenerated by hand schedule: GQA softmax row-sum moved to the matrix pipe (16x16x32 selector MFMA), in-place batched fmamk/exp, cross-half max only on rescale path; baseline loa
# speedup vs baseline: 1.0128x; 1.0128x over previous
; DI int tid_() { int t = threadIdx.x; asm volatile("" : "+v"(t)); return t; }
; template <int DQK, bool BAND, int QT> ...
;     ...
;   const int tid = tid_(), lane = tid & 63, w = tid >> 6, h = lane >> 5, ql = lane & 31;
;   float* bias_l = (float*)(lds + 2 * ST);
;   if (BAND) { if (tid < 129) bias_l[tid] = bias_g[tid]; }
;   bf16x8 qf[QT][NKS];
; #pragma unroll
;   for (int qt = 0; qt < QT; ++qt)
; #pragma unroll
;     for (int ks = 0; ks < NKS; ++ks) qf[qt][ks] = *(const bf16x8*)(Q + (size_t)(w * WQ + qt * 32 + ql) * DQK + ks * 16 + h * 8);
;   f32x16 o[2][QT];
; #pragma unroll
;   for (int a = 0; a < 2; ++a)
; #pragma unroll
;     for (int b = 0; b < QT; ++b)
; #pragma unroll
;       for (int r = 0; r < 16; ++r) o[a][b][r] = 0.f;
;   float m[QT], l[QT];
; #pragma unroll
;   for (int qt = 0; qt < QT; ++qt) { m[qt] = -1e30f; l[qt] = 0.f; }
;   u32x4 rk[NKL], rv[2];
;   const int vrow0 = tid >> 3, vch = tid & 7;
;   unsigned klds[NKL];
; #pragma unroll
;   for (int i = 0; i < NKL; ++i) { const int idx = tid + i * 256, kr = idx / KV4, kc = idx - kr * KV4; klds[i] = kr * KROW + kc * 16; }
;   const unsigned koff0 = (unsigned)tid * 16u;
;   const unsigned voff0 = (unsigned)(vrow0 * ldv + vch * 8) * 2u, vstep = (unsigned)(32 * ldv) * 2u;
;   const unsigned vlds0 = KST + vrow0 * LROW + vch * 16;
;   auto gload = [&](int kt) {
;     const char* kb = (const char*)Kp + (size_t)kt * (DQK * 2);
;     const char* vb = (const char*)Vt + (size_t)kt * 2;
; #pragma unroll
;     for (int i = 0; i < NKL; ++i) rk[i] = *(const u32x4*)(kb + (koff0 + i * 4096u));
; #pragma unroll
;     for (int i = 0; i < 2; ++i) rv[i] = *(const u32x4*)(vb + (voff0 + i * vstep));
;   };
;   auto lstore = [&](char* st) {
; #pragma unroll
;     for (int i = 0; i < NKL; ++i) *(u32x4*)(st + klds[i]) = rk[i];
; #pragma unroll
;     for (int i = 0; i < 2; ++i) *(u32x4*)(st + vlds0 + i * 32 * LROW) = rv[i];
;   };
;   gload(kbeg);
;   lstore(lds);
;   __syncthreads();
;   const int pr = (ql & ~12) | ((ql & 4) << 1) | ((ql & 8) >> 1);
;   const int k_rd = pr * KROW + h * 16;
;   const int v_rd = KST + ql * LROW + h * 16;
.LBB0_826:
	s_and_b64 vcc, exec, s[0:1]
	s_cbranch_vccz .LBB0_838
	v_readlane_b32 s0, v249, 58
	s_sub_i32 s0, s26, s0
	s_ashr_i32 s1, s0, 3
	s_ashr_i32 s7, s0, 31
	s_abs_i32 s0, s1
	v_readlane_b32 s2, v248, 3
	s_mul_hi_u32 s2, s0, s2
	v_readlane_b32 s5, v248, 2
	s_mul_i32 s3, s2, s5
	s_sub_i32 s0, s0, s3
	s_add_i32 s3, s2, 1
	s_sub_i32 s4, s0, s5
	s_cmp_ge_u32 s0, s5
	s_cselect_b32 s2, s3, s2
	s_cselect_b32 s0, s4, s0
	s_add_i32 s3, s2, 1
	s_cmp_ge_u32 s0, s5
	s_cselect_b32 s0, s3, s2
	s_xor_b32 s40, s0, s7
	s_sub_i32 s0, s40, s7
	s_lshl_b32 s2, s0, s60
	s_sub_i32 s1, s1, s2
	s_lshl_b32 s2, s0, 3
	v_readlane_b32 s3, v249, 31
	s_or_b32 s2, s2, s3
	s_lshl_b32 s4, s0, 1
	v_readlane_b32 s41, v250, 44
	s_ashr_i32 s3, s2, 31
	s_or_b32 s26, s4, s41
	s_lshl_b32 s4, s1, 8
	s_lshl_b64 s[2:3], s[2:3], s20
	s_ashr_i32 s27, s26, 31
	s_ashr_i32 s5, s4, 31
	s_add_u32 s2, s2, s4
	s_addc_u32 s3, s3, s5
	s_lshl_b64 s[2:3], s[2:3], 7
	v_readlane_b32 s1, v250, 53
	s_add_u32 s34, s1, s2
	v_readlane_b32 s1, v250, 54
	s_addc_u32 s35, s1, s3
	v_readlane_b32 s1, v248, 1
	s_lshl_b64 s[2:3], s[26:27], s1
	v_readlane_b32 s1, v250, 55
	s_add_u32 s38, s1, s2
	v_readlane_b32 s1, v250, 56
	v_mov_b32_e32 v5, v199
	s_addc_u32 s39, s1, s3
	v_readlane_b32 s1, v249, 61
	v_readlane_b32 s6, v249, 63
	v_lshlrev_b32_e32 v2, 4, v5
	v_ashrrev_i32_e32 v18, 3, v5
	s_mul_hi_i32 s27, s26, s1
	s_mul_i32 s26, s26, s1
	v_and_b32_e32 v4, 0x70, v2
	v_mul_lo_u32 v0, v18, s6
	v_bfe_u32 v196, v5, 5, 1
	v_and_b32_e32 v180, 0xffffffdf, v5
	s_lshl_b64 s[26:27], s[26:27], 1
	v_readlane_b32 s42, v250, 28
	v_or_b32_e32 v6, v4, v0
	s_waitcnt vmcnt(16)
	v_or_b32_e32 v178, 32, v5
	v_lshlrev_b32_e32 v0, 4, v196
	v_ashrrev_i32_e32 v181, 31, v180
	v_readlane_b32 s43, v250, 29
	s_add_u32 s26, s42, s26
	v_ashrrev_i32_e32 v179, 31, v178
	v_lshlrev_b64 v[12:13], 7, v[180:181]
	v_lshl_add_u64 v[16:17], s[34:35], 0, v[0:1]
	s_addc_u32 s27, s43, s27
	v_lshlrev_b64 v[14:15], 7, v[178:179]
	v_lshl_add_u64 v[12:13], v[16:17], 0, v[12:13]
	v_add_u32_e32 v8, 0x1000, v2
	global_load_dwordx4 v[130:133], v2, s[38:39]
	global_load_dwordx4 v[134:137], v8, s[38:39]
	v_add_u32_e32 v10, s1, v6
	global_load_dwordx4 v[138:141], v6, s[26:27]
	global_load_dwordx4 v[142:145], v10, s[26:27]
	v_lshl_add_u64 v[14:15], v[16:17], 0, v[14:15]
	global_load_dwordx4 v[146:149], v[12:13], off
	global_load_dwordx4 v[150:153], v[12:13], off offset:32
	global_load_dwordx4 v[154:157], v[12:13], off offset:64
	global_load_dwordx4 v[158:161], v[12:13], off offset:96
	global_load_dwordx4 v[162:165], v[14:15], off
	global_load_dwordx4 v[166:169], v[14:15], off offset:32
	global_load_dwordx4 v[170:173], v[14:15], off offset:64
	global_load_dwordx4 v[174:177], v[14:15], off offset:96
	v_ashrrev_i32_e32 v19, 31, v5
	v_add_u32_e32 v20, 0x100, v5
	v_lshrrev_b32_e32 v13, 29, v19
	v_ashrrev_i32_e32 v14, 31, v20
	v_add_u32_e32 v13, v5, v13
	v_lshrrev_b32_e32 v14, 29, v14
	v_mad_u64_u32 v[182:183], s[26:27], v18, s16, v[4:5]
	v_ashrrev_i32_e32 v13, 3, v13
	v_add_u32_e32 v4, v20, v14
	v_lshlrev_b32_e32 v16, 7, v13
	v_ashrrev_i32_e32 v17, 3, v4
	v_lshlrev_b32_e32 v15, 4, v20
	v_sub_u32_e32 v4, v2, v16
	v_lshlrev_b32_e32 v16, 7, v17
	v_mad_u64_u32 v[184:185], s[26:27], v13, s16, v[4:5]
	v_sub_u32_e32 v4, v15, v16
	v_mad_u64_u32 v[186:187], s[26:27], v17, s16, v[4:5]
	s_lshl_b32 s26, s40, 1
	s_or_b32 s26, s41, s26
	s_lshl_b32 s7, s7, 1
	s_sub_i32 s7, s26, s7
	v_readlane_b32 s26, v248, 4
	v_and_b32_e32 v12, 31, v5
	v_add_u32_e32 v4, 0, v184
	s_mul_hi_i32 s27, s26, s7
	s_mul_i32 s7, s26, s7
	v_add_u32_e32 v14, 0, v182
	v_add_u32_e32 v13, 0, v186
	v_mul_u32_u24_e32 v183, 0x90, v12
	v_lshlrev_b32_e32 v12, 1, v5
	s_add_u32 s26, s7, 0x179d5980
	s_waitcnt vmcnt(11)
	ds_write_b128 v4, v[130:133]
	s_waitcnt vmcnt(10)
	ds_write_b128 v13, v[134:137]
	s_waitcnt vmcnt(9)
	ds_write_b128 v14, v[138:141] offset:9216
	s_waitcnt vmcnt(8)
	ds_write_b128 v14, v[142:145] offset:13824
	v_and_b32_e32 v4, 19, v5
	v_lshrrev_b32_e32 v5, 1, v5
	v_and_b32_e32 v12, 8, v12
	v_and_b32_e32 v5, 4, v5
	s_addc_u32 s27, s27, 0
	v_or3_b32 v4, v4, v12, v5
	v_cmp_lt_i32_e32 vcc, v221, v220
	s_add_u32 s2, s2, 0x175d7900
	v_mov_b32_e32 v3, v1
	v_mov_b32_e32 v9, v1
	v_mov_b32_e32 v7, v1
	v_mov_b32_e32 v11, v1
	v_mul_u32_u24_e32 v185, 0x90, v4
	v_cndmask_b32_e32 v4, v219, v221, vcc
	s_addc_u32 s3, s3, 0
	v_mov_b32_e32 v50, v1
	v_mov_b32_e32 v51, v1
	v_lshlrev_b32_e32 v179, 2, v4
	v_lshl_add_u64 v[188:189], s[26:27], 0, v[6:7]
	v_lshl_add_u64 v[190:191], s[26:27], 0, v[10:11]
	v_lshl_add_u64 v[192:193], s[2:3], 0, v[2:3]
	v_lshl_add_u64 v[194:195], s[2:3], 0, v[8:9]
	v_mov_b32_e32 v52, v1
	v_mov_b32_e32 v53, v1
	v_mov_b32_e32 v54, v1
	v_mov_b32_e32 v55, v1
	v_mov_b32_e32 v56, v1
	v_mov_b32_e32 v57, v1
	v_mov_b32_e32 v58, v1
	v_mov_b32_e32 v59, v1
	v_mov_b32_e32 v60, v1
	v_mov_b32_e32 v61, v1
	v_mov_b32_e32 v62, v1
	v_mov_b32_e32 v63, v1
	v_mov_b32_e32 v64, v1
	v_mov_b32_e32 v65, v1
	v_mov_b64_e32 v[18:19], v[50:51]
	v_mov_b64_e32 v[34:35], v[50:51]
	v_mov_b64_e32 v[2:3], v[50:51]
	s_mov_b32 s1, 0
	s_mov_b32 s6, 64
	v_mov_b32_e32 v197, 0xf149f2ca
	v_mov_b32_e32 v187, 0
	v_mov_b32_e32 v181, 0
	v_mov_b32_e32 v202, 0xf149f2ca
	v_mov_b64_e32 v[20:21], v[52:53]
	v_mov_b64_e32 v[22:23], v[54:55]
	v_mov_b64_e32 v[24:25], v[56:57]
	v_mov_b64_e32 v[26:27], v[58:59]
	v_mov_b64_e32 v[28:29], v[60:61]
	v_mov_b64_e32 v[30:31], v[62:63]
	v_mov_b64_e32 v[32:33], v[64:65]
	v_mov_b64_e32 v[36:37], v[52:53]
	v_mov_b64_e32 v[38:39], v[54:55]
	v_mov_b64_e32 v[40:41], v[56:57]
	v_mov_b64_e32 v[42:43], v[58:59]
	v_mov_b64_e32 v[44:45], v[60:61]
	v_mov_b64_e32 v[46:47], v[62:63]
	v_mov_b64_e32 v[48:49], v[64:65]
	v_mov_b64_e32 v[4:5], v[52:53]
	v_mov_b64_e32 v[6:7], v[54:55]
	v_mov_b64_e32 v[8:9], v[56:57]
	v_mov_b64_e32 v[10:11], v[58:59]
	v_mov_b64_e32 v[12:13], v[60:61]
	v_mov_b64_e32 v[14:15], v[62:63]
	v_mov_b64_e32 v[16:17], v[64:65]
	v_add_u32_e32 v185, v185, v0
	v_add_u32_e32 v183, v183, v0
	v_mbcnt_lo_u32_b32 v254, -1, 0
	v_mbcnt_hi_u32_b32 v254, -1, v254
	v_and_b32_e32 v255, 15, v254
	v_lshrrev_b32_e32 v253, 4, v254
	v_and_b32_e32 v253, 1, v253
	v_cmp_eq_u32_e32 vcc, v255, v253
	v_mov_b32_e32 v253, 0x3f803f80
	s_nop 1
	v_cndmask_b32_e32 v244, 0, v253, vcc
	v_mov_b32_e32 v245, v244
	v_mov_b32_e32 v246, v244
	v_mov_b32_e32 v247, v244
	v_mov_b32_e32 v236, 0
	v_mov_b32_e32 v237, 0
	v_mov_b32_e32 v238, 0
	v_mov_b32_e32 v239, 0
	v_mov_b32_e32 v240, 0
	v_mov_b32_e32 v241, 0
	v_mov_b32_e32 v242, 0
	v_mov_b32_e32 v243, 0
	s_waitcnt vmcnt(0) lgkmcnt(0)
	s_barrier
; #define MFMA(a, b, c) __builtin_amdgcn_mfma_f32_32x32x16_bf16((a), (b), (c), 0, 0, 0)
; template <int DQK, bool BAND, int QT> ...
;     ...
;   for (int kt = kbeg; kt < kend; kt += 64, ++it) {
;     const char* st = lds + (it & 1) * ST;
;     const bool more = (kt + 64 < kend);
;     if (more) gload(kt + 64);
;     bool need = true;
;     if (BAND) need = (kt + 63 >= qw0 - 64) && (kt <= qw0 + WQ - 1 + 64);
;     if (need) {
;       f32x16 s[2][QT];
; #pragma unroll
;       for (int a = 0; a < 2; ++a)
; #pragma unroll
;         for (int b = 0; b < QT; ++b)
; #pragma unroll
;           for (int r = 0; r < 16; ++r) s[a][b][r] = 0.f;
; #pragma unroll
;       for (int ks = 0; ks < NKS; ++ks) {
;         const bf16x8 k0 = *(const bf16x8*)(st + k_rd + ks * 32);
;         const bf16x8 k1 = *(const bf16x8*)(st + k_rd + 32 * KROW + ks * 32);
; #pragma unroll
;         for (int qt = 0; qt < QT; ++qt) {
;           s[0][qt] = MFMA(k0, qf[qt][ks], s[0][qt]);
;           s[1][qt] = MFMA(k1, qf[qt][ks], s[1][qt]);
;         }
;       }
;       __builtin_amdgcn_s_setprio(3);
;       bf16x8 pf[QT][4];
;       const float cc = BAND ? 1.0f : scale_log2;
;       const float th = BAND ? 8.0f : 8.0f / scale_log2;
; #pragma unroll
;       for (int qt = 0; qt < QT; ++qt) {
;         if (BAND) {
; #pragma unroll
;           for (int a = 0; a < 2; ++a)
; #pragma unroll
;             for (int r = 0; r < 16; ++r) {
;               const int kidx = kt + 32 * a + (r & 7) + 8 * h + 16 * (r >> 3);
;               const int rel = kidx - (qw0 + qt * 32 + ql);
;               const bool ok = (rel >= -64) && (rel <= 64);
;               const int bi = ok ? rel + 64 : 0;
;               s[a][qt][r] = ok ? fmaf(s[a][qt][r], scale_log2, bias_l[bi]) : -1e30f;
;             }
;         }
;         float mx = s[0][qt][0];
; #pragma unroll
;         for (int r = 1; r < 16; ++r) mx = fmaxf(mx, s[0][qt][r]);
; #pragma unroll
;         for (int r = 0; r < 16; ++r) mx = fmaxf(mx, s[1][qt][r]);
;         mx = fmaxf(mx, __shfl_xor(mx, 32));
;         if (__builtin_amdgcn_ballot_w64(mx > m[qt] + th) != 0) {
;           const float mn = fmaxf(m[qt], mx);
;           const float alpha = __builtin_amdgcn_exp2f((m[qt] - mn) * cc);
;           m[qt] = mn;
;           l[qt] *= alpha;
; #pragma unroll
;           for (int r = 0; r < 16; ++r) { o[0][qt][r] *= alpha; o[1][qt][r] *= alpha; }
;         }
.Lgqa_top:
	s_cmp_lt_u32 s6, s19
	s_cselect_b64 s[2:3], -1, 0
	s_cbranch_scc0 .Lgqa_noload
	v_lshl_add_u64 v[254:255], s[94:95], 0, v[192:193]
	global_load_dwordx4 v[130:133], v[254:255], off
	v_lshl_add_u64 v[254:255], s[94:95], 0, v[194:195]
	global_load_dwordx4 v[134:137], v[254:255], off
	v_lshl_add_u64 v[254:255], s[94:95], 0, v[188:189]
	global_load_dwordx4 v[138:141], v[254:255], off
	v_lshl_add_u64 v[254:255], s[94:95], 0, v[190:191]
	global_load_dwordx4 v[142:145], v[254:255], off
.Lgqa_noload:
	ds_read_b128 v[206:209], v185
	ds_read_b128 v[210:213], v185 offset:4608
	ds_read_b128 v[214:217], v185 offset:32
	ds_read_b128 v[232:235], v185 offset:4640
	s_waitcnt lgkmcnt(3)
	v_mfma_f32_32x32x16_bf16 v[82:97], v[206:209], v[146:149], 0
	v_mfma_f32_32x32x16_bf16 v[114:129], v[206:209], v[162:165], 0
	ds_read_b128 v[206:209], v185 offset:64
	s_waitcnt lgkmcnt(3)
	v_mfma_f32_32x32x16_bf16 v[66:81], v[210:213], v[146:149], 0
	v_mfma_f32_32x32x16_bf16 v[98:113], v[210:213], v[162:165], 0
	ds_read_b128 v[210:213], v185 offset:4672
	s_waitcnt lgkmcnt(3)
	v_mfma_f32_32x32x16_bf16 v[82:97], v[214:217], v[150:153], v[82:97]
	v_mfma_f32_32x32x16_bf16 v[114:129], v[214:217], v[166:169], v[114:129]
	ds_read_b128 v[214:217], v185 offset:96
	s_waitcnt lgkmcnt(3)
	v_mfma_f32_32x32x16_bf16 v[66:81], v[232:235], v[150:153], v[66:81]
	v_mfma_f32_32x32x16_bf16 v[98:113], v[232:235], v[166:169], v[98:113]
	ds_read_b128 v[232:235], v185 offset:4704
	s_waitcnt lgkmcnt(3)
	v_mfma_f32_32x32x16_bf16 v[82:97], v[206:209], v[154:157], v[82:97]
	v_mfma_f32_32x32x16_bf16 v[114:129], v[206:209], v[170:173], v[114:129]
	s_waitcnt lgkmcnt(2)
	v_mfma_f32_32x32x16_bf16 v[66:81], v[210:213], v[154:157], v[66:81]
	v_mfma_f32_32x32x16_bf16 v[98:113], v[210:213], v[170:173], v[98:113]
	s_waitcnt lgkmcnt(1)
	v_mfma_f32_32x32x16_bf16 v[82:97], v[214:217], v[158:161], v[82:97]
	v_mfma_f32_32x32x16_bf16 v[114:129], v[214:217], v[174:177], v[114:129]
	s_waitcnt lgkmcnt(0)
	v_mfma_f32_32x32x16_bf16 v[66:81], v[232:235], v[158:161], v[66:81]
	v_mfma_f32_32x32x16_bf16 v[98:113], v[232:235], v[174:177], v[98:113]
	s_waitcnt vmcnt(0)
	s_nop 6
	v_max_f32_e32 v203, v82, v83
	v_max_f32_e32 v253, v114, v115
	v_max3_f32 v203, v203, v84, v85
	v_max3_f32 v253, v253, v116, v117
	v_max3_f32 v203, v203, v86, v87
	v_max3_f32 v253, v253, v118, v119
	v_max3_f32 v203, v203, v88, v89
	v_max3_f32 v253, v253, v120, v121
	v_max3_f32 v203, v203, v90, v91
	v_max3_f32 v253, v253, v122, v123
	v_max3_f32 v203, v203, v92, v93
	v_max3_f32 v253, v253, v124, v125
	v_max3_f32 v203, v203, v94, v95
	v_max3_f32 v253, v253, v126, v127
	v_max3_f32 v203, v203, v96, v97
	v_max3_f32 v253, v253, v128, v129
	v_max3_f32 v203, v203, v66, v67
	v_max3_f32 v253, v253, v98, v99
	v_max3_f32 v203, v203, v68, v69
	v_max3_f32 v253, v253, v100, v101
	v_max3_f32 v203, v203, v70, v71
	v_max3_f32 v253, v253, v102, v103
	v_max3_f32 v203, v203, v72, v73
	v_max3_f32 v253, v253, v104, v105
	v_max3_f32 v203, v203, v74, v75
	v_max3_f32 v253, v253, v106, v107
	v_max3_f32 v203, v203, v76, v77
	v_max3_f32 v253, v253, v108, v109
	v_max3_f32 v203, v203, v78, v79
	v_max3_f32 v253, v253, v110, v111
	v_max3_f32 v203, v203, v80, v81
	v_max3_f32 v253, v253, v112, v113
	v_add_f32_e32 v254, 0x42317218, v197
	v_cmp_gt_f32_e32 vcc, v203, v254
	s_cbranch_vccz .Lgqa_nr0
	ds_bpermute_b32 v254, v179, v203
	s_waitcnt lgkmcnt(0)
	v_max_f32_e32 v254, v254, v254
	v_max_f32_e32 v203, v203, v254
	v_max_f32_e32 v254, v197, v197
	v_max_f32_e32 v203, v254, v203
	v_sub_f32_e32 v197, v197, v203
	v_mul_f32_e32 v197, 0x3e38aa3b, v197
	v_exp_f32_e32 v254, v197
	v_mov_b32_e32 v197, v203
	v_pk_mul_f32 v[64:65], v[64:65], v[254:255] op_sel_hi:[1,0]
	v_pk_mul_f32 v[62:63], v[62:63], v[254:255] op_sel_hi:[1,0]
	v_pk_mul_f32 v[60:61], v[60:61], v[254:255] op_sel_hi:[1,0]
	v_pk_mul_f32 v[58:59], v[58:59], v[254:255] op_sel_hi:[1,0]
	v_pk_mul_f32 v[56:57], v[56:57], v[254:255] op_sel_hi:[1,0]
	v_pk_mul_f32 v[54:55], v[54:55], v[254:255] op_sel_hi:[1,0]
	v_pk_mul_f32 v[52:53], v[52:53], v[254:255] op_sel_hi:[1,0]
	v_pk_mul_f32 v[50:51], v[50:51], v[254:255] op_sel_hi:[1,0]
	v_pk_mul_f32 v[48:49], v[48:49], v[254:255] op_sel_hi:[1,0]
	v_pk_mul_f32 v[46:47], v[46:47], v[254:255] op_sel_hi:[1,0]
	v_pk_mul_f32 v[44:45], v[44:45], v[254:255] op_sel_hi:[1,0]
	v_pk_mul_f32 v[42:43], v[42:43], v[254:255] op_sel_hi:[1,0]
	v_pk_mul_f32 v[40:41], v[40:41], v[254:255] op_sel_hi:[1,0]
	v_pk_mul_f32 v[38:39], v[38:39], v[254:255] op_sel_hi:[1,0]
	v_pk_mul_f32 v[36:37], v[36:37], v[254:255] op_sel_hi:[1,0]
	v_pk_mul_f32 v[34:35], v[34:35], v[254:255] op_sel_hi:[1,0]
	v_pk_mul_f32 v[240:241], v[240:241], v[254:255] op_sel_hi:[1,0]
	v_pk_mul_f32 v[242:243], v[242:243], v[254:255] op_sel_hi:[1,0]
.Lgqa_nr0:
	v_add_f32_e32 v254, 0x42317218, v202
	v_cmp_gt_f32_e32 vcc, v253, v254
	s_cbranch_vccz .Lgqa_nr1
	ds_bpermute_b32 v254, v179, v253
	s_waitcnt lgkmcnt(0)
	v_max_f32_e32 v254, v254, v254
	v_max_f32_e32 v253, v253, v254
	v_max_f32_e32 v254, v202, v202
	v_max_f32_e32 v253, v254, v253
	v_sub_f32_e32 v202, v202, v253
	v_mul_f32_e32 v202, 0x3e38aa3b, v202
	v_exp_f32_e32 v254, v202
	v_mov_b32_e32 v202, v253
	v_pk_mul_f32 v[32:33], v[32:33], v[254:255] op_sel_hi:[1,0]
	v_pk_mul_f32 v[30:31], v[30:31], v[254:255] op_sel_hi:[1,0]
	v_pk_mul_f32 v[28:29], v[28:29], v[254:255] op_sel_hi:[1,0]
	v_pk_mul_f32 v[26:27], v[26:27], v[254:255] op_sel_hi:[1,0]
	v_pk_mul_f32 v[24:25], v[24:25], v[254:255] op_sel_hi:[1,0]
	v_pk_mul_f32 v[22:23], v[22:23], v[254:255] op_sel_hi:[1,0]
	v_pk_mul_f32 v[20:21], v[20:21], v[254:255] op_sel_hi:[1,0]
	v_pk_mul_f32 v[18:19], v[18:19], v[254:255] op_sel_hi:[1,0]
	v_pk_mul_f32 v[16:17], v[16:17], v[254:255] op_sel_hi:[1,0]
	v_pk_mul_f32 v[14:15], v[14:15], v[254:255] op_sel_hi:[1,0]
	v_pk_mul_f32 v[12:13], v[12:13], v[254:255] op_sel_hi:[1,0]
	v_pk_mul_f32 v[10:11], v[10:11], v[254:255] op_sel_hi:[1,0]
	v_pk_mul_f32 v[8:9], v[8:9], v[254:255] op_sel_hi:[1,0]
	v_pk_mul_f32 v[6:7], v[6:7], v[254:255] op_sel_hi:[1,0]
	v_pk_mul_f32 v[4:5], v[4:5], v[254:255] op_sel_hi:[1,0]
	v_pk_mul_f32 v[2:3], v[2:3], v[254:255] op_sel_hi:[1,0]
	v_pk_mul_f32 v[236:237], v[236:237], v[254:255] op_sel_hi:[1,0]
	v_pk_mul_f32 v[238:239], v[238:239], v[254:255] op_sel_hi:[1,0]
; DI unsigned pk2(float a, float b) { f32x2 v = {a, b}; bf16x2_t r = __builtin_convertvector(v, bf16x2_t); return __builtin_bit_cast(unsigned, r); }
; template <int DQK, bool BAND, int QT> ...
;     ...
;   auto lstore = [&](char* st) {
; #pragma unroll
;     for (int i = 0; i < NKL; ++i) *(u32x4*)(st + klds[i]) = rk[i];
; #pragma unroll
;     for (int i = 0; i < 2; ++i) *(u32x4*)(st + vlds0 + i * 32 * LROW) = rv[i];
;   };
;     ...
;         const float mc = -m[qt] * cc;
;         float ls = 0.f;
; #pragma unroll
;         for (int a = 0; a < 2; ++a) {
; #pragma unroll
;           for (int r = 0; r < 16; ++r) { const float pv = __builtin_amdgcn_exp2f(fmaf(s[a][qt][r], cc, mc)); s[a][qt][r] = pv; ls += pv; }
; #pragma unroll
;           for (int s2 = 0; s2 < 2; ++s2) {
;             u32x4 pk;
;             pk.x = pk2(s[a][qt][8 * s2 + 0], s[a][qt][8 * s2 + 1]);
;             pk.y = pk2(s[a][qt][8 * s2 + 2], s[a][qt][8 * s2 + 3]);
;             pk.z = pk2(s[a][qt][8 * s2 + 4], s[a][qt][8 * s2 + 5]);
;             pk.w = pk2(s[a][qt][8 * s2 + 6], s[a][qt][8 * s2 + 7]);
;             pf[qt][a * 2 + s2] = __builtin_bit_cast(bf16x8, pk);
;           }
;         }
;         l[qt] += ls;
;       }
;       __builtin_amdgcn_s_setprio(0);
;       if (more) lstore(lds + ((it + 1) & 1) * ST);
; #pragma unroll
;       for (int ks = 0; ks < 4; ++ks) {
;         const bf16x8 v0 = *(const bf16x8*)(st + v_rd + ks * 32);
;         const bf16x8 v1 = *(const bf16x8*)(st + v_rd + 32 * LROW + ks * 32);
.Lgqa_nr1:
	s_andn2_b64 vcc, exec, s[2:3]
	s_cbranch_vccnz .Lgqa_nostage
	s_andn2_b32 s2, 1, s1
	s_mulk_i32 s2, 0x4800
	v_add_u32_e32 v204, s2, v184
	s_waitcnt vmcnt(3)
	ds_write_b128 v204, v[130:133]
	v_add_u32_e32 v204, s2, v186
	s_waitcnt vmcnt(2)
	ds_write_b128 v204, v[134:137]
	v_add_u32_e32 v204, s2, v182
	s_waitcnt vmcnt(1)
	ds_write_b128 v204, v[138:141] offset:9216
	s_waitcnt vmcnt(0)
	ds_write_b128 v204, v[142:145] offset:13824
.Lgqa_nostage:
	v_mul_f32_e32 v254, 0xbe38aa3b, v197
	v_mul_f32_e32 v255, 0xbe38aa3b, v202
	v_fmamk_f32 v82, v82, 0x3e38aa3b, v254
	v_fmamk_f32 v114, v114, 0x3e38aa3b, v255
	v_fmamk_f32 v83, v83, 0x3e38aa3b, v254
	v_fmamk_f32 v115, v115, 0x3e38aa3b, v255
	v_fmamk_f32 v84, v84, 0x3e38aa3b, v254
	v_fmamk_f32 v116, v116, 0x3e38aa3b, v255
	v_fmamk_f32 v85, v85, 0x3e38aa3b, v254
	v_fmamk_f32 v117, v117, 0x3e38aa3b, v255
	v_fmamk_f32 v86, v86, 0x3e38aa3b, v254
	v_fmamk_f32 v118, v118, 0x3e38aa3b, v255
	v_fmamk_f32 v87, v87, 0x3e38aa3b, v254
	v_fmamk_f32 v119, v119, 0x3e38aa3b, v255
	v_fmamk_f32 v88, v88, 0x3e38aa3b, v254
	v_fmamk_f32 v120, v120, 0x3e38aa3b, v255
	v_fmamk_f32 v89, v89, 0x3e38aa3b, v254
	v_fmamk_f32 v121, v121, 0x3e38aa3b, v255
	v_exp_f32_e32 v82, v82
	v_exp_f32_e32 v114, v114
	v_exp_f32_e32 v83, v83
	v_exp_f32_e32 v115, v115
	v_exp_f32_e32 v84, v84
	v_exp_f32_e32 v116, v116
	v_exp_f32_e32 v85, v85
	v_exp_f32_e32 v117, v117
	v_exp_f32_e32 v86, v86
	v_exp_f32_e32 v118, v118
	v_exp_f32_e32 v87, v87
	v_exp_f32_e32 v119, v119
	v_exp_f32_e32 v88, v88
	v_exp_f32_e32 v120, v120
	v_exp_f32_e32 v89, v89
	v_exp_f32_e32 v121, v121
	v_fmamk_f32 v90, v90, 0x3e38aa3b, v254
	v_fmamk_f32 v122, v122, 0x3e38aa3b, v255
	v_fmamk_f32 v91, v91, 0x3e38aa3b, v254
	v_fmamk_f32 v123, v123, 0x3e38aa3b, v255
	v_fmamk_f32 v92, v92, 0x3e38aa3b, v254
	v_fmamk_f32 v124, v124, 0x3e38aa3b, v255
	v_fmamk_f32 v93, v93, 0x3e38aa3b, v254
	v_fmamk_f32 v125, v125, 0x3e38aa3b, v255
	v_fmamk_f32 v94, v94, 0x3e38aa3b, v254
	v_fmamk_f32 v126, v126, 0x3e38aa3b, v255
	v_fmamk_f32 v95, v95, 0x3e38aa3b, v254
	v_fmamk_f32 v127, v127, 0x3e38aa3b, v255
	v_fmamk_f32 v96, v96, 0x3e38aa3b, v254
	v_fmamk_f32 v128, v128, 0x3e38aa3b, v255
	v_fmamk_f32 v97, v97, 0x3e38aa3b, v254
	v_fmamk_f32 v129, v129, 0x3e38aa3b, v255
	v_exp_f32_e32 v90, v90
	v_exp_f32_e32 v122, v122
	v_exp_f32_e32 v91, v91
	v_exp_f32_e32 v123, v123
	v_exp_f32_e32 v92, v92
	v_exp_f32_e32 v124, v124
	v_exp_f32_e32 v93, v93
	v_exp_f32_e32 v125, v125
	v_exp_f32_e32 v94, v94
	v_exp_f32_e32 v126, v126
	v_exp_f32_e32 v95, v95
	v_exp_f32_e32 v127, v127
	v_exp_f32_e32 v96, v96
	v_exp_f32_e32 v128, v128
	v_exp_f32_e32 v97, v97
	v_exp_f32_e32 v129, v129
	v_cvt_pk_bf16_f32 v82, v82, v83
	v_cvt_pk_bf16_f32 v114, v114, v115
	v_cvt_pk_bf16_f32 v83, v84, v85
	v_cvt_pk_bf16_f32 v115, v116, v117
	v_cvt_pk_bf16_f32 v84, v86, v87
	v_cvt_pk_bf16_f32 v116, v118, v119
	v_cvt_pk_bf16_f32 v85, v88, v89
	v_cvt_pk_bf16_f32 v117, v120, v121
	v_fmamk_f32 v66, v66, 0x3e38aa3b, v254
	v_fmamk_f32 v98, v98, 0x3e38aa3b, v255
	v_fmamk_f32 v67, v67, 0x3e38aa3b, v254
	v_fmamk_f32 v99, v99, 0x3e38aa3b, v255
	v_fmamk_f32 v68, v68, 0x3e38aa3b, v254
	v_fmamk_f32 v100, v100, 0x3e38aa3b, v255
	v_fmamk_f32 v69, v69, 0x3e38aa3b, v254
	v_fmamk_f32 v101, v101, 0x3e38aa3b, v255
	v_fmamk_f32 v70, v70, 0x3e38aa3b, v254
	v_fmamk_f32 v102, v102, 0x3e38aa3b, v255
	v_fmamk_f32 v71, v71, 0x3e38aa3b, v254
	v_fmamk_f32 v103, v103, 0x3e38aa3b, v255
	v_fmamk_f32 v72, v72, 0x3e38aa3b, v254
	v_fmamk_f32 v104, v104, 0x3e38aa3b, v255
	v_fmamk_f32 v73, v73, 0x3e38aa3b, v254
	v_fmamk_f32 v105, v105, 0x3e38aa3b, v255
	v_exp_f32_e32 v66, v66
	v_exp_f32_e32 v98, v98
	v_exp_f32_e32 v67, v67
	v_exp_f32_e32 v99, v99
	v_exp_f32_e32 v68, v68
	v_exp_f32_e32 v100, v100
	v_exp_f32_e32 v69, v69
	v_exp_f32_e32 v101, v101
	v_exp_f32_e32 v70, v70
	v_exp_f32_e32 v102, v102
	v_exp_f32_e32 v71, v71
	v_exp_f32_e32 v103, v103
	v_exp_f32_e32 v72, v72
	v_exp_f32_e32 v104, v104
	v_exp_f32_e32 v73, v73
	v_exp_f32_e32 v105, v105
	v_cvt_pk_bf16_f32 v90, v90, v91
	v_cvt_pk_bf16_f32 v122, v122, v123
	v_cvt_pk_bf16_f32 v91, v92, v93
	v_cvt_pk_bf16_f32 v123, v124, v125
	v_cvt_pk_bf16_f32 v92, v94, v95
	v_cvt_pk_bf16_f32 v124, v126, v127
	v_cvt_pk_bf16_f32 v93, v96, v97
	v_cvt_pk_bf16_f32 v125, v128, v129
	v_fmamk_f32 v74, v74, 0x3e38aa3b, v254
	v_fmamk_f32 v106, v106, 0x3e38aa3b, v255
	v_fmamk_f32 v75, v75, 0x3e38aa3b, v254
	v_fmamk_f32 v107, v107, 0x3e38aa3b, v255
	v_fmamk_f32 v76, v76, 0x3e38aa3b, v254
	v_fmamk_f32 v108, v108, 0x3e38aa3b, v255
	v_fmamk_f32 v77, v77, 0x3e38aa3b, v254
	v_fmamk_f32 v109, v109, 0x3e38aa3b, v255
	v_fmamk_f32 v78, v78, 0x3e38aa3b, v254
	v_fmamk_f32 v110, v110, 0x3e38aa3b, v255
	v_fmamk_f32 v79, v79, 0x3e38aa3b, v254
	v_fmamk_f32 v111, v111, 0x3e38aa3b, v255
	v_fmamk_f32 v80, v80, 0x3e38aa3b, v254
	v_fmamk_f32 v112, v112, 0x3e38aa3b, v255
	v_fmamk_f32 v81, v81, 0x3e38aa3b, v254
	v_fmamk_f32 v113, v113, 0x3e38aa3b, v255
	v_exp_f32_e32 v74, v74
	v_exp_f32_e32 v106, v106
	v_exp_f32_e32 v75, v75
	v_exp_f32_e32 v107, v107
	v_exp_f32_e32 v76, v76
	v_exp_f32_e32 v108, v108
	v_exp_f32_e32 v77, v77
	v_exp_f32_e32 v109, v109
	v_exp_f32_e32 v78, v78
	v_exp_f32_e32 v110, v110
	v_exp_f32_e32 v79, v79
	v_exp_f32_e32 v111, v111
	v_exp_f32_e32 v80, v80
	v_exp_f32_e32 v112, v112
	v_exp_f32_e32 v81, v81
	v_exp_f32_e32 v113, v113
	v_cvt_pk_bf16_f32 v66, v66, v67
	v_cvt_pk_bf16_f32 v98, v98, v99
	v_cvt_pk_bf16_f32 v67, v68, v69
	v_cvt_pk_bf16_f32 v99, v100, v101
	v_cvt_pk_bf16_f32 v68, v70, v71
	v_cvt_pk_bf16_f32 v100, v102, v103
	v_cvt_pk_bf16_f32 v69, v72, v73
	v_cvt_pk_bf16_f32 v101, v104, v105
	v_cvt_pk_bf16_f32 v74, v74, v75
	v_cvt_pk_bf16_f32 v106, v106, v107
	v_cvt_pk_bf16_f32 v75, v76, v77
	v_cvt_pk_bf16_f32 v107, v108, v109
	v_cvt_pk_bf16_f32 v76, v78, v79
	v_cvt_pk_bf16_f32 v108, v110, v111
	v_cvt_pk_bf16_f32 v77, v80, v81
	v_cvt_pk_bf16_f32 v109, v112, v113
	ds_read_b128 v[86:89], v183 offset:9216
	ds_read_b128 v[94:97], v183 offset:13824
	ds_read_b128 v[70:73], v183 offset:9248
	ds_read_b128 v[78:81], v183 offset:13856
	ds_read_b128 v[118:121], v183 offset:9280
	ds_read_b128 v[126:129], v183 offset:13888
	ds_read_b128 v[102:105], v183 offset:9312
	ds_read_b128 v[110:113], v183 offset:13920
	s_waitcnt lgkmcnt(7)
; #define MFMA(a, b, c) __builtin_amdgcn_mfma_f32_32x32x16_bf16((a), (b), (c), 0, 0, 0)
; template <int DQK, bool BAND, int QT> ...
;     ...
; #pragma unroll
;       for (int ks = 0; ks < 4; ++ks) {
;         const bf16x8 v0 = *(const bf16x8*)(st + v_rd + ks * 32);
;         const bf16x8 v1 = *(const bf16x8*)(st + v_rd + 32 * LROW + ks * 32);
; #pragma unroll
;         for (int qt = 0; qt < QT; ++qt) {
;           o[0][qt] = MFMA(v0, pf[qt][ks], o[0][qt]);
;           o[1][qt] = MFMA(v1, pf[qt][ks], o[1][qt]);
;         }
;       }
;     } else {
;       if (more) lstore(lds + ((it + 1) & 1) * ST);
;     }
;     __syncthreads();
;   }
; #pragma unroll
;   for (int qt = 0; qt < QT; ++qt) {
;     const float lt = l[qt] + __shfl_xor(l[qt], 32);
;     const float inv = __builtin_amdgcn_rcpf(lt);
	v_mfma_f32_32x32x16_bf16 v[50:65], v[86:89], v[82:85], v[50:65]
	v_mfma_f32_32x32x16_bf16 v[18:33], v[86:89], v[114:117], v[18:33]
	s_waitcnt lgkmcnt(6)
	v_mfma_f32_32x32x16_bf16 v[34:49], v[94:97], v[82:85], v[34:49]
	v_mfma_f32_32x32x16_bf16 v[2:17], v[94:97], v[114:117], v[2:17]
	v_mfma_f32_16x16x32_bf16 v[240:243], v[244:247], v[82:85], v[240:243]
	v_mfma_f32_16x16x32_bf16 v[236:239], v[244:247], v[114:117], v[236:239]
	v_lshl_add_u64 v[192:193], v[192:193], 0, s[88:89]
	v_lshl_add_u64 v[194:195], v[194:195], 0, s[88:89]
	v_lshl_add_u64 v[188:189], v[188:189], 0, s[76:77]
	v_lshl_add_u64 v[190:191], v[190:191], 0, s[76:77]
	s_waitcnt lgkmcnt(5)
	v_mfma_f32_32x32x16_bf16 v[50:65], v[70:73], v[90:93], v[50:65]
	v_mfma_f32_32x32x16_bf16 v[18:33], v[70:73], v[122:125], v[18:33]
	s_waitcnt lgkmcnt(4)
	v_mfma_f32_32x32x16_bf16 v[34:49], v[78:81], v[90:93], v[34:49]
	v_mfma_f32_32x32x16_bf16 v[2:17], v[78:81], v[122:125], v[2:17]
	v_mfma_f32_16x16x32_bf16 v[240:243], v[244:247], v[90:93], v[240:243]
	v_mfma_f32_16x16x32_bf16 v[236:239], v[244:247], v[122:125], v[236:239]
	s_waitcnt lgkmcnt(3)
	v_mfma_f32_32x32x16_bf16 v[50:65], v[118:121], v[66:69], v[50:65]
	v_mfma_f32_32x32x16_bf16 v[18:33], v[118:121], v[98:101], v[18:33]
	s_waitcnt lgkmcnt(2)
	v_mfma_f32_32x32x16_bf16 v[34:49], v[126:129], v[66:69], v[34:49]
	v_mfma_f32_32x32x16_bf16 v[2:17], v[126:129], v[98:101], v[2:17]
	v_mfma_f32_16x16x32_bf16 v[240:243], v[244:247], v[66:69], v[240:243]
	v_mfma_f32_16x16x32_bf16 v[236:239], v[244:247], v[98:101], v[236:239]
	s_bitcmp1_b32 s1, 0
	s_cselect_b32 s7, -1, 1
	s_mulk_i32 s7, 0x4800
	v_add_u32_e32 v185, s7, v185
	v_add_u32_e32 v183, s7, v183
	s_add_i32 s1, s1, 1
	s_add_i32 s6, s6, 64
	s_waitcnt lgkmcnt(0)
	s_barrier
	v_mfma_f32_32x32x16_bf16 v[50:65], v[102:105], v[74:77], v[50:65]
	v_mfma_f32_32x32x16_bf16 v[18:33], v[102:105], v[106:109], v[18:33]
	v_mfma_f32_32x32x16_bf16 v[34:49], v[110:113], v[74:77], v[34:49]
	v_mfma_f32_32x32x16_bf16 v[2:17], v[110:113], v[106:109], v[2:17]
	v_mfma_f32_16x16x32_bf16 v[240:243], v[244:247], v[74:77], v[240:243]
	v_mfma_f32_16x16x32_bf16 v[236:239], v[244:247], v[106:109], v[236:239]
	s_cmp_lg_u32 s21, s1
	s_cbranch_scc1 .Lgqa_top
	s_nop 7
	v_mbcnt_lo_u32_b32 v254, -1, 0
	v_mbcnt_hi_u32_b32 v254, -1, v254
	v_and_b32_e32 v255, 15, v254
	v_lshlrev_b32_e32 v255, 2, v255
	ds_bpermute_b32 v203, v255, v240
	ds_bpermute_b32 v253, v255, v241
	s_waitcnt lgkmcnt(0)
	v_cmp_gt_u32_e32 vcc, 16, v254
	s_nop 1
	v_cndmask_b32_e32 v187, v253, v203, vcc
	v_cmp_gt_u32_e32 vcc, 32, v254
	s_nop 1
	v_cndmask_b32_e32 v187, 0, v187, vcc
	ds_bpermute_b32 v203, v255, v236
	ds_bpermute_b32 v253, v255, v237
	s_waitcnt lgkmcnt(0)
	v_cmp_gt_u32_e32 vcc, 16, v254
	s_nop 1
	v_cndmask_b32_e32 v181, v253, v203, vcc
	v_cmp_gt_u32_e32 vcc, 32, v254
	s_nop 1
	v_cndmask_b32_e32 v181, 0, v181, vcc

; DI int tid_() { int t = threadIdx.x; asm volatile("" : "+v"(t)); return t; }
; template <int DQK, bool BAND, int QT> ...
;     ...
;   const int tid = tid_(), lane = tid & 63, w = tid >> 6, h = lane >> 5, ql = lane & 31;
;   float* bias_l = (float*)(lds + 2 * ST);
;   if (BAND) { if (tid < 129) bias_l[tid] = bias_g[tid]; }
;   bf16x8 qf[QT][NKS];
; #pragma unroll
;   for (int qt = 0; qt < QT; ++qt)
; #pragma unroll
;     for (int ks = 0; ks < NKS; ++ks) qf[qt][ks] = *(const bf16x8*)(Q + (size_t)(w * WQ + qt * 32 + ql) * DQK + ks * 16 + h * 8);
;   f32x16 o[2][QT];
; #pragma unroll
;   for (int a = 0; a < 2; ++a)
; #pragma unroll
;     for (int b = 0; b < QT; ++b)
; #pragma unroll
;       for (int r = 0; r < 16; ++r) o[a][b][r] = 0.f;
;   float m[QT], l[QT];
; #pragma unroll
;   for (int qt = 0; qt < QT; ++qt) { m[qt] = -1e30f; l[qt] = 0.f; }
;   u32x4 rk[NKL], rv[2];
;   const int vrow0 = tid >> 3, vch = tid & 7;
;   unsigned klds[NKL];
; #pragma unroll
;   for (int i = 0; i < NKL; ++i) { const int idx = tid + i * 256, kr = idx / KV4, kc = idx - kr * KV4; klds[i] = kr * KROW + kc * 16; }
;   const unsigned koff0 = (unsigned)tid * 16u;
;   const unsigned voff0 = (unsigned)(vrow0 * ldv + vch * 8) * 2u, vstep = (unsigned)(32 * ldv) * 2u;
;   const unsigned vlds0 = KST + vrow0 * LROW + vch * 16;
;   auto gload = [&](int kt) {
;     const char* kb = (const char*)Kp + (size_t)kt * (DQK * 2);
;     const char* vb = (const char*)Vt + (size_t)kt * 2;
; #pragma unroll
;     for (int i = 0; i < NKL; ++i) rk[i] = *(const u32x4*)(kb + (koff0 + i * 4096u));
; #pragma unroll
;     for (int i = 0; i < 2; ++i) rv[i] = *(const u32x4*)(vb + (voff0 + i * vstep));
;   };
;   auto lstore = [&](char* st) {
; #pragma unroll
;     for (int i = 0; i < NKL; ++i) *(u32x4*)(st + klds[i]) = rk[i];
; #pragma unroll
;     for (int i = 0; i < 2; ++i) *(u32x4*)(st + vlds0 + i * 32 * LROW) = rv[i];
;   };
;   gload(kbeg);
;   lstore(lds);
;   __syncthreads();
;   const int pr = (ql & ~12) | ((ql & 4) << 1) | ((ql & 8) >> 1);
;   const int k_rd = pr * KROW + h * 16;
;   const int v_rd = KST + ql * LROW + h * 16;
.LBB0_839:
	s_andn2_b64 vcc, exec, s[0:1]
	s_cbranch_vccnz .LBB0_664
	s_abs_i32 s0, s25
	v_readlane_b32 s1, v248, 3
	s_mul_hi_u32 s1, s0, s1
	v_readlane_b32 s4, v248, 2
	s_mul_i32 s2, s1, s4
	s_sub_i32 s0, s0, s2
	s_ashr_i32 s7, s25, 31
	s_add_i32 s2, s1, 1
	s_sub_i32 s3, s0, s4
	s_cmp_ge_u32 s0, s4
	s_cselect_b32 s1, s2, s1
	s_cselect_b32 s0, s3, s0
	s_add_i32 s2, s1, 1
	s_cmp_ge_u32 s0, s4
	s_cselect_b32 s0, s2, s1
	s_xor_b32 s38, s0, s7
	s_sub_i32 s0, s38, s7
	s_lshl_b32 s1, s0, s60
	s_lshl_b32 s2, s0, 3
	v_readlane_b32 s40, v249, 31
	s_sub_i32 s1, s25, s1
	s_or_b32 s26, s2, s40
	s_ashr_i32 s27, s26, 31
	s_lshl_b32 s4, s1, 8
	s_lshl_b64 s[34:35], s[26:27], s20
	s_ashr_i32 s5, s4, 31
	s_add_u32 s1, s34, s4
	s_addc_u32 s2, s35, s5
	s_mulk_i32 s2, 0xc0
	s_mul_hi_u32 s3, s1, 0xc0
	s_add_i32 s3, s3, s2
	s_mulk_i32 s1, 0xc0
	v_readlane_b32 s42, v250, 40
	v_readlane_b32 s43, v250, 41
	s_add_u32 s2, s42, s1
	s_mul_i32 s1, s35, 0xc0
	s_mul_hi_u32 s6, s34, 0xc0
	s_addc_u32 s3, s43, s3
	s_add_i32 s25, s6, s1
	s_mul_i32 s39, s34, 0xc0
	v_readlane_b32 s34, v250, 38
	v_readlane_b32 s35, v250, 39
	s_add_u32 s34, s34, s39
	v_mov_b32_e32 v2, v199
	s_addc_u32 s35, s35, s25
	v_readlane_b32 s1, v249, 61
	v_lshlrev_b32_e32 v4, 4, v2
	global_load_dwordx4 v[130:133], v4, s[34:35]
	v_add_u32_e32 v8, 0x1000, v4
	global_load_dwordx4 v[134:137], v8, s[34:35]
	s_mul_hi_i32 s27, s26, s1
	s_mul_i32 s26, s26, s1
	s_lshl_b64 s[26:27], s[26:27], 1
	v_readlane_b32 s42, v250, 36
	v_ashrrev_i32_e32 v3, 3, v2
	v_readlane_b32 s6, v249, 63
	v_readlane_b32 s43, v250, 37
	s_add_u32 s26, s42, s26
	v_and_b32_e32 v6, 0x70, v4
	v_mul_lo_u32 v0, v3, s6
	s_addc_u32 s27, s43, s27
	v_add_u32_e32 v10, 0x2000, v4
	v_or_b32_e32 v12, v6, v0
	v_bfe_u32 v230, v2, 5, 1
	global_load_dwordx4 v[138:141], v10, s[34:35]
	v_add_u32_e32 v14, s1, v12
	global_load_dwordx4 v[146:149], v12, s[26:27]
	global_load_dwordx4 v[170:173], v14, s[26:27]
	v_lshlrev_b32_e32 v0, 4, v230
	v_and_b32_e32 v204, 0xffffffdf, v2
	v_lshl_add_u64 v[16:17], s[2:3], 0, v[0:1]
	s_movk_i32 s1, 0xc0
	v_or_b32_e32 v202, 32, v2
	v_mad_i64_i32 v[18:19], s[2:3], v204, s1, v[16:17]
	v_mad_i64_i32 v[16:17], s[2:3], v202, s1, v[16:17]
	global_load_dwordx4 v[142:145], v[18:19], off
	global_load_dwordx4 v[150:153], v[18:19], off offset:32
	global_load_dwordx4 v[154:157], v[18:19], off offset:64
	global_load_dwordx4 v[158:161], v[18:19], off offset:96
	global_load_dwordx4 v[162:165], v[18:19], off offset:128
	global_load_dwordx4 v[166:169], v[18:19], off offset:160
	global_load_dwordx4 v[174:177], v[16:17], off
	global_load_dwordx4 v[178:181], v[16:17], off offset:32
	global_load_dwordx4 v[182:185], v[16:17], off offset:64
	global_load_dwordx4 v[186:189], v[16:17], off offset:96
	global_load_dwordx4 v[190:193], v[16:17], off offset:128
	global_load_dwordx4 v[194:197], v[16:17], off offset:160
	s_mov_b32 s1, 0x2aaaaaab
	v_mul_hi_i32 v5, v2, s1
	v_lshrrev_b32_e32 v7, 31, v5
	v_ashrrev_i32_e32 v5, 1, v5
	v_add_u32_e32 v5, v5, v7
	s_movk_i32 s6, 0xd0
	v_mad_u64_u32 v[16:17], s[2:3], v5, -12, v[2:3]
	v_mul_lo_u32 v5, v5, s6
	v_lshl_add_u32 v231, v16, 4, v5
	v_add_u32_e32 v16, 0x100, v2
	v_mul_hi_i32 v5, v16, s1
	v_lshrrev_b32_e32 v7, 31, v5
	v_ashrrev_i32_e32 v5, 1, v5
	v_add_u32_e32 v5, v5, v7
	v_mad_u64_u32 v[16:17], s[2:3], v5, -12, v[16:17]
	v_mul_lo_u32 v5, v5, s6
	v_lshl_add_u32 v232, v16, 4, v5
	v_add_u32_e32 v16, 0x200, v2
	v_mul_hi_i32 v5, v16, s1
	v_lshrrev_b32_e32 v7, 31, v5
	v_ashrrev_i32_e32 v5, 1, v5
	v_add_u32_e32 v5, v5, v7
	v_mad_u64_u32 v[16:17], s[2:3], v5, -12, v[16:17]
	v_mul_lo_u32 v5, v5, s6
	v_add_u32_e32 v7, 0, v231
	v_lshl_add_u32 v233, v16, 4, v5
	v_mov_b32_e32 v13, v1
	v_mov_b32_e32 v15, v1
	v_cmp_lt_i32_e32 vcc, v221, v220
	v_mov_b32_e32 v5, v1
	v_mov_b32_e32 v9, v1
	v_mov_b32_e32 v11, v1
	v_mov_b32_e32 v50, v1
	v_mov_b32_e32 v51, v1
	v_mov_b32_e32 v52, v1
	v_mov_b32_e32 v53, v1
	v_mov_b32_e32 v54, v1
	v_mov_b32_e32 v55, v1
	v_mov_b32_e32 v56, v1
	v_mov_b32_e32 v57, v1
	v_mov_b32_e32 v58, v1
	v_mov_b32_e32 v59, v1
	v_mov_b32_e32 v60, v1
	v_mov_b32_e32 v61, v1
	v_mov_b32_e32 v62, v1
	v_mov_b32_e32 v63, v1
	s_waitcnt vmcnt(16)
	ds_write_b128 v7, v[130:133]
	v_add_u32_e32 v7, 0, v232
	s_waitcnt vmcnt(15)
	ds_write_b128 v7, v[134:137]
	v_add_u32_e32 v7, 0, v233
	v_mad_u64_u32 v[206:207], s[2:3], v3, s16, v[6:7]
	s_lshl_b32 s2, s38, 3
	s_or_b32 s2, s40, s2
	s_lshl_b32 s3, s7, 3
	v_add_u32_e32 v3, 0, v206
	s_sub_i32 s2, s2, s3
	v_readlane_b32 s7, v248, 4
	s_mul_hi_i32 s3, s7, s2
	s_mul_i32 s2, s7, s2
	v_lshlrev_b32_e32 v6, 1, v2
	s_add_u32 s2, s2, 0x10d35980
	v_and_b32_e32 v6, 8, v6
	s_waitcnt vmcnt(14)
	ds_write_b128 v7, v[138:141]
	s_waitcnt vmcnt(13)
	ds_write_b128 v3, v[146:149] offset:13312
	s_waitcnt vmcnt(12)
	ds_write_b128 v3, v[170:173] offset:17920
	v_and_b32_e32 v3, 31, v2
	v_mul_u32_u24_e32 v234, 0x90, v3
	v_and_b32_e32 v3, 19, v2
	v_lshrrev_b32_e32 v2, 1, v2
	v_and_b32_e32 v2, 4, v2
	s_addc_u32 s3, s3, 0
	v_or3_b32 v2, v3, v6, v2
	v_lshl_add_u64 v[208:209], s[2:3], 0, v[12:13]
	v_lshl_add_u64 v[210:211], s[2:3], 0, v[14:15]
	s_add_u32 s2, s39, 0xf538900
	v_mul_u32_u24_e32 v235, 0xd0, v2
	v_cndmask_b32_e32 v2, v219, v221, vcc
	s_addc_u32 s3, s25, 0
	v_lshlrev_b32_e32 v203, 2, v2
	v_lshl_add_u64 v[212:213], s[2:3], 0, v[4:5]
	v_lshl_add_u64 v[214:215], s[2:3], 0, v[8:9]
	v_lshl_add_u64 v[216:217], s[2:3], 0, v[10:11]
	v_mov_b32_e32 v64, v1
	v_mov_b32_e32 v65, v1
	v_mov_b64_e32 v[18:19], v[50:51]
	v_mov_b64_e32 v[34:35], v[50:51]
	v_mov_b64_e32 v[2:3], v[50:51]
	s_mov_b32 s1, 0
	s_mov_b32 s6, 64
	v_mov_b32_e32 v237, 0xf149f2ca
	v_mov_b32_e32 v236, 0
	v_mov_b32_e32 v207, 0
	v_mov_b32_e32 v238, 0xf149f2ca
	v_mov_b64_e32 v[20:21], v[52:53]
	v_mov_b64_e32 v[22:23], v[54:55]
	v_mov_b64_e32 v[24:25], v[56:57]
	v_mov_b64_e32 v[26:27], v[58:59]
	v_mov_b64_e32 v[28:29], v[60:61]
	v_mov_b64_e32 v[30:31], v[62:63]
	v_mov_b64_e32 v[32:33], v[64:65]
	v_mov_b64_e32 v[36:37], v[52:53]
	v_mov_b64_e32 v[38:39], v[54:55]
	v_mov_b64_e32 v[40:41], v[56:57]
	v_mov_b64_e32 v[42:43], v[58:59]
	v_mov_b64_e32 v[44:45], v[60:61]
	v_mov_b64_e32 v[46:47], v[62:63]
	v_mov_b64_e32 v[48:49], v[64:65]
	v_mov_b64_e32 v[4:5], v[52:53]
	v_mov_b64_e32 v[6:7], v[54:55]
	v_mov_b64_e32 v[8:9], v[56:57]
	v_mov_b64_e32 v[10:11], v[58:59]
	v_mov_b64_e32 v[12:13], v[60:61]
	v_mov_b64_e32 v[14:15], v[62:63]
	v_mov_b64_e32 v[16:17], v[64:65]
	v_add_u32_e32 v235, v235, v0
	v_add_u32_e32 v234, v234, v0
	s_waitcnt vmcnt(0) lgkmcnt(0)
	s_barrier
; #define MFMA(a, b, c) __builtin_amdgcn_mfma_f32_32x32x16_bf16((a), (b), (c), 0, 0, 0)
; template <int DQK, bool BAND, int QT> ...
;     ...
;   for (int kt = kbeg; kt < kend; kt += 64, ++it) {
;     const char* st = lds + (it & 1) * ST;
;     const bool more = (kt + 64 < kend);
;     if (more) gload(kt + 64);
;     bool need = true;
;     if (BAND) need = (kt + 63 >= qw0 - 64) && (kt <= qw0 + WQ - 1 + 64);
;     if (need) {
;       f32x16 s[2][QT];
; #pragma unroll
;       for (int a = 0; a < 2; ++a)
; #pragma unroll
;         for (int b = 0; b < QT; ++b)
; #pragma unroll
;           for (int r = 0; r < 16; ++r) s[a][b][r] = 0.f;
; #pragma unroll
;       for (int ks = 0; ks < NKS; ++ks) {
;         const bf16x8 k0 = *(const bf16x8*)(st + k_rd + ks * 32);
;         const bf16x8 k1 = *(const bf16x8*)(st + k_rd + 32 * KROW + ks * 32);
; #pragma unroll
;         for (int qt = 0; qt < QT; ++qt) {
;           s[0][qt] = MFMA(k0, qf[qt][ks], s[0][qt]);
;           s[1][qt] = MFMA(k1, qf[qt][ks], s[1][qt]);
;         }
;       }
;       __builtin_amdgcn_s_setprio(3);
;       bf16x8 pf[QT][4];
;       const float cc = BAND ? 1.0f : scale_log2;
;       const float th = BAND ? 8.0f : 8.0f / scale_log2;
; #pragma unroll
;       for (int qt = 0; qt < QT; ++qt) {
;         if (BAND) {
; #pragma unroll
;           for (int a = 0; a < 2; ++a)
; #pragma unroll
;             for (int r = 0; r < 16; ++r) {
;               const int kidx = kt + 32 * a + (r & 7) + 8 * h + 16 * (r >> 3);
;               const int rel = kidx - (qw0 + qt * 32 + ql);
;               const bool ok = (rel >= -64) && (rel <= 64);
;               const int bi = ok ? rel + 64 : 0;
;               s[a][qt][r] = ok ? fmaf(s[a][qt][r], scale_log2, bias_l[bi]) : -1e30f;
;             }
;         }
;         float mx = s[0][qt][0];
; #pragma unroll
;         for (int r = 1; r < 16; ++r) mx = fmaxf(mx, s[0][qt][r]);
; #pragma unroll
;         for (int r = 0; r < 16; ++r) mx = fmaxf(mx, s[1][qt][r]);
;         mx = fmaxf(mx, __shfl_xor(mx, 32));
;         if (__builtin_amdgcn_ballot_w64(mx > m[qt] + th) != 0) {
;           const float mn = fmaxf(m[qt], mx);
;           const float alpha = __builtin_amdgcn_exp2f((m[qt] - mn) * cc);
;           m[qt] = mn;
;           l[qt] *= alpha;
; #pragma unroll
;           for (int r = 0; r < 16; ++r) { o[0][qt][r] *= alpha; o[1][qt][r] *= alpha; }
;         }
.Lmla_top:
	s_cmp_lt_u32 s6, s19
	s_cselect_b64 s[2:3], -1, 0
	s_cbranch_scc0 .Lmla_noload
	v_lshl_add_u64 v[254:255], s[94:95], 0, v[212:213]
	global_load_dwordx4 v[130:133], v[254:255], off
	v_lshl_add_u64 v[254:255], s[94:95], 0, v[214:215]
	global_load_dwordx4 v[134:137], v[254:255], off
	v_lshl_add_u64 v[254:255], s[94:95], 0, v[216:217]
	global_load_dwordx4 v[138:141], v[254:255], off
	v_lshl_add_u64 v[254:255], s[94:95], 0, v[208:209]
	global_load_dwordx4 v[146:149], v[254:255], off
	v_lshl_add_u64 v[254:255], s[94:95], 0, v[210:211]
	global_load_dwordx4 v[170:173], v[254:255], off
.Lmla_noload:
	ds_read_b128 v[102:105], v235
	ds_read_b128 v[98:101], v235 offset:6656
	ds_read_b128 v[240:243], v235 offset:32
	ds_read_b128 v[244:247], v235 offset:6688
	s_waitcnt lgkmcnt(3)
	v_mfma_f32_32x32x16_bf16 v[82:97], v[102:105], v[142:145], 0
	v_mfma_f32_32x32x16_bf16 v[114:129], v[102:105], v[174:177], 0
	s_waitcnt lgkmcnt(2)
	v_mfma_f32_32x32x16_bf16 v[66:81], v[98:101], v[142:145], 0
	v_mfma_f32_32x32x16_bf16 v[98:113], v[98:101], v[174:177], 0
	s_waitcnt lgkmcnt(1)
	v_mfma_f32_32x32x16_bf16 v[82:97], v[240:243], v[150:153], v[82:97]
	v_mfma_f32_32x32x16_bf16 v[114:129], v[240:243], v[178:181], v[114:129]
	ds_read_b128 v[240:243], v235 offset:64
	s_waitcnt lgkmcnt(1)
	v_mfma_f32_32x32x16_bf16 v[66:81], v[244:247], v[150:153], v[66:81]
	v_mfma_f32_32x32x16_bf16 v[98:113], v[244:247], v[178:181], v[98:113]
	ds_read_b128 v[244:247], v235 offset:6720
	s_waitcnt lgkmcnt(1)
	v_mfma_f32_32x32x16_bf16 v[82:97], v[240:243], v[154:157], v[82:97]
	v_mfma_f32_32x32x16_bf16 v[114:129], v[240:243], v[182:185], v[114:129]
	ds_read_b128 v[240:243], v235 offset:96
	s_waitcnt lgkmcnt(1)
	v_mfma_f32_32x32x16_bf16 v[66:81], v[244:247], v[154:157], v[66:81]
	v_mfma_f32_32x32x16_bf16 v[98:113], v[244:247], v[182:185], v[98:113]
	ds_read_b128 v[244:247], v235 offset:6752
	s_waitcnt lgkmcnt(1)
	v_mfma_f32_32x32x16_bf16 v[82:97], v[240:243], v[158:161], v[82:97]
	v_mfma_f32_32x32x16_bf16 v[114:129], v[240:243], v[186:189], v[114:129]
	ds_read_b128 v[240:243], v235 offset:128
	s_waitcnt lgkmcnt(1)
	v_mfma_f32_32x32x16_bf16 v[66:81], v[244:247], v[158:161], v[66:81]
	v_mfma_f32_32x32x16_bf16 v[98:113], v[244:247], v[186:189], v[98:113]
	ds_read_b128 v[244:247], v235 offset:6784
	s_waitcnt lgkmcnt(1)
	v_mfma_f32_32x32x16_bf16 v[82:97], v[240:243], v[162:165], v[82:97]
	v_mfma_f32_32x32x16_bf16 v[114:129], v[240:243], v[190:193], v[114:129]
	ds_read_b128 v[240:243], v235 offset:160
	s_waitcnt lgkmcnt(1)
	v_mfma_f32_32x32x16_bf16 v[66:81], v[244:247], v[162:165], v[66:81]
	v_mfma_f32_32x32x16_bf16 v[98:113], v[244:247], v[190:193], v[98:113]
	ds_read_b128 v[244:247], v235 offset:6816
	s_waitcnt lgkmcnt(1)
	v_mfma_f32_32x32x16_bf16 v[82:97], v[240:243], v[166:169], v[82:97]
	v_mfma_f32_32x32x16_bf16 v[114:129], v[240:243], v[194:197], v[114:129]
	s_waitcnt lgkmcnt(0)
	v_mfma_f32_32x32x16_bf16 v[66:81], v[244:247], v[166:169], v[66:81]
	v_mfma_f32_32x32x16_bf16 v[98:113], v[244:247], v[194:197], v[98:113]
	s_waitcnt vmcnt(0)
	s_nop 6
	v_max_f32_e32 v239, v82, v83
	v_max_f32_e32 v253, v114, v115
	v_max3_f32 v239, v239, v84, v85
	v_max3_f32 v253, v253, v116, v117
	v_max3_f32 v239, v239, v86, v87
	v_max3_f32 v253, v253, v118, v119
	v_max3_f32 v239, v239, v88, v89
	v_max3_f32 v253, v253, v120, v121
	v_max3_f32 v239, v239, v90, v91
	v_max3_f32 v253, v253, v122, v123
	v_max3_f32 v239, v239, v92, v93
	v_max3_f32 v253, v253, v124, v125
	v_max3_f32 v239, v239, v94, v95
	v_max3_f32 v253, v253, v126, v127
	v_max3_f32 v239, v239, v96, v97
	v_max3_f32 v253, v253, v128, v129
	v_max3_f32 v239, v239, v66, v67
	v_max3_f32 v253, v253, v98, v99
	v_max3_f32 v239, v239, v68, v69
	v_max3_f32 v253, v253, v100, v101
	v_max3_f32 v239, v239, v70, v71
	v_max3_f32 v253, v253, v102, v103
	v_max3_f32 v239, v239, v72, v73
	v_max3_f32 v253, v253, v104, v105
	v_max3_f32 v239, v239, v74, v75
	v_max3_f32 v253, v253, v106, v107
	v_max3_f32 v239, v239, v76, v77
	v_max3_f32 v253, v253, v108, v109
	v_max3_f32 v239, v239, v78, v79
	v_max3_f32 v253, v253, v110, v111
	v_max3_f32 v239, v239, v80, v81
	v_max3_f32 v253, v253, v112, v113
	v_add_f32_e32 v254, 0x4259535f, v237
	v_cmp_gt_f32_e32 vcc, v239, v254
	s_cbranch_vccz .Lmla_nr0
	ds_bpermute_b32 v254, v203, v239
	s_waitcnt lgkmcnt(0)
	v_max_f32_e32 v254, v254, v254
	v_max_f32_e32 v239, v239, v254
	v_max_f32_e32 v254, v237, v237
	v_max_f32_e32 v239, v254, v239
	v_sub_f32_e32 v237, v237, v239
	v_mul_f32_e32 v237, 0x3e16c740, v237
	v_exp_f32_e32 v254, v237
	v_mov_b32_e32 v237, v239
	v_pk_mul_f32 v[64:65], v[64:65], v[254:255] op_sel_hi:[1,0]
	v_pk_mul_f32 v[62:63], v[62:63], v[254:255] op_sel_hi:[1,0]
	v_pk_mul_f32 v[60:61], v[60:61], v[254:255] op_sel_hi:[1,0]
	v_pk_mul_f32 v[58:59], v[58:59], v[254:255] op_sel_hi:[1,0]
	v_pk_mul_f32 v[56:57], v[56:57], v[254:255] op_sel_hi:[1,0]
	v_pk_mul_f32 v[54:55], v[54:55], v[254:255] op_sel_hi:[1,0]
	v_pk_mul_f32 v[52:53], v[52:53], v[254:255] op_sel_hi:[1,0]
	v_pk_mul_f32 v[50:51], v[50:51], v[254:255] op_sel_hi:[1,0]
	v_pk_mul_f32 v[48:49], v[48:49], v[254:255] op_sel_hi:[1,0]
	v_pk_mul_f32 v[46:47], v[46:47], v[254:255] op_sel_hi:[1,0]
	v_pk_mul_f32 v[44:45], v[44:45], v[254:255] op_sel_hi:[1,0]
	v_pk_mul_f32 v[42:43], v[42:43], v[254:255] op_sel_hi:[1,0]
	v_pk_mul_f32 v[40:41], v[40:41], v[254:255] op_sel_hi:[1,0]
	v_pk_mul_f32 v[38:39], v[38:39], v[254:255] op_sel_hi:[1,0]
	v_pk_mul_f32 v[36:37], v[36:37], v[254:255] op_sel_hi:[1,0]
	v_pk_mul_f32 v[34:35], v[34:35], v[254:255] op_sel_hi:[1,0]
	v_mul_f32_e32 v236, v236, v254
; DI unsigned pk2(float a, float b) { f32x2 v = {a, b}; bf16x2_t r = __builtin_convertvector(v, bf16x2_t); return __builtin_bit_cast(unsigned, r); }
; template <int DQK, bool BAND, int QT> ...
;     ...
;   auto lstore = [&](char* st) {
; #pragma unroll
;     for (int i = 0; i < NKL; ++i) *(u32x4*)(st + klds[i]) = rk[i];
; #pragma unroll
;     for (int i = 0; i < 2; ++i) *(u32x4*)(st + vlds0 + i * 32 * LROW) = rv[i];
;   };
;     ...
;         if (__builtin_amdgcn_ballot_w64(mx > m[qt] + th) != 0) {
;           const float mn = fmaxf(m[qt], mx);
;           const float alpha = __builtin_amdgcn_exp2f((m[qt] - mn) * cc);
;           m[qt] = mn;
;           l[qt] *= alpha;
; #pragma unroll
;           for (int r = 0; r < 16; ++r) { o[0][qt][r] *= alpha; o[1][qt][r] *= alpha; }
;         }
;         const float mc = -m[qt] * cc;
;         float ls = 0.f;
; #pragma unroll
;         for (int a = 0; a < 2; ++a) {
; #pragma unroll
;           for (int r = 0; r < 16; ++r) { const float pv = __builtin_amdgcn_exp2f(fmaf(s[a][qt][r], cc, mc)); s[a][qt][r] = pv; ls += pv; }
; #pragma unroll
;           for (int s2 = 0; s2 < 2; ++s2) {
;             u32x4 pk;
;             pk.x = pk2(s[a][qt][8 * s2 + 0], s[a][qt][8 * s2 + 1]);
;             pk.y = pk2(s[a][qt][8 * s2 + 2], s[a][qt][8 * s2 + 3]);
;             pk.z = pk2(s[a][qt][8 * s2 + 4], s[a][qt][8 * s2 + 5]);
;             pk.w = pk2(s[a][qt][8 * s2 + 6], s[a][qt][8 * s2 + 7]);
;             pf[qt][a * 2 + s2] = __builtin_bit_cast(bf16x8, pk);
;           }
;         }
;         l[qt] += ls;
.Lmla_nr0:
	v_add_f32_e32 v254, 0x4259535f, v238
	v_cmp_gt_f32_e32 vcc, v253, v254
	s_cbranch_vccz .Lmla_nr1
	ds_bpermute_b32 v254, v203, v253
	s_waitcnt lgkmcnt(0)
	v_max_f32_e32 v254, v254, v254
	v_max_f32_e32 v253, v253, v254
	v_max_f32_e32 v254, v238, v238
	v_max_f32_e32 v253, v254, v253
	v_sub_f32_e32 v238, v238, v253
	v_mul_f32_e32 v238, 0x3e16c740, v238
	v_exp_f32_e32 v254, v238
	v_mov_b32_e32 v238, v253
	v_pk_mul_f32 v[32:33], v[32:33], v[254:255] op_sel_hi:[1,0]
	v_pk_mul_f32 v[30:31], v[30:31], v[254:255] op_sel_hi:[1,0]
	v_pk_mul_f32 v[28:29], v[28:29], v[254:255] op_sel_hi:[1,0]
	v_pk_mul_f32 v[26:27], v[26:27], v[254:255] op_sel_hi:[1,0]
	v_pk_mul_f32 v[24:25], v[24:25], v[254:255] op_sel_hi:[1,0]
	v_pk_mul_f32 v[22:23], v[22:23], v[254:255] op_sel_hi:[1,0]
	v_pk_mul_f32 v[20:21], v[20:21], v[254:255] op_sel_hi:[1,0]
	v_pk_mul_f32 v[18:19], v[18:19], v[254:255] op_sel_hi:[1,0]
	v_pk_mul_f32 v[16:17], v[16:17], v[254:255] op_sel_hi:[1,0]
	v_pk_mul_f32 v[14:15], v[14:15], v[254:255] op_sel_hi:[1,0]
	v_pk_mul_f32 v[12:13], v[12:13], v[254:255] op_sel_hi:[1,0]
	v_pk_mul_f32 v[10:11], v[10:11], v[254:255] op_sel_hi:[1,0]
	v_pk_mul_f32 v[8:9], v[8:9], v[254:255] op_sel_hi:[1,0]
	v_pk_mul_f32 v[6:7], v[6:7], v[254:255] op_sel_hi:[1,0]
	v_pk_mul_f32 v[4:5], v[4:5], v[254:255] op_sel_hi:[1,0]
	v_pk_mul_f32 v[2:3], v[2:3], v[254:255] op_sel_hi:[1,0]
	v_mul_f32_e32 v207, v207, v254
.Lmla_nr1:
	s_andn2_b64 vcc, exec, s[2:3]
	s_cbranch_vccnz .Lmla_nostage
	s_andn2_b32 s2, 1, s1
	s_mulk_i32 s2, 0x5800
	v_add_u32_e32 v240, s2, v231
	s_waitcnt vmcnt(4)
	ds_write_b128 v240, v[130:133]
	v_add_u32_e32 v240, s2, v232
	s_waitcnt vmcnt(3)
	ds_write_b128 v240, v[134:137]
	v_add_u32_e32 v240, s2, v233
	s_waitcnt vmcnt(2)
	ds_write_b128 v240, v[138:141]
	v_add_u32_e32 v240, s2, v206
	s_waitcnt vmcnt(1)
	ds_write_b128 v240, v[146:149] offset:13312
	s_waitcnt vmcnt(0)
	ds_write_b128 v240, v[170:173] offset:17920
.Lmla_nostage:
	v_mul_f32_e32 v254, 0xbe16c740, v237
	v_mul_f32_e32 v255, 0xbe16c740, v238
	v_fmamk_f32 v82, v82, 0x3e16c740, v254
	v_fmamk_f32 v114, v114, 0x3e16c740, v255
	v_fmamk_f32 v83, v83, 0x3e16c740, v254
	v_fmamk_f32 v115, v115, 0x3e16c740, v255
	v_fmamk_f32 v84, v84, 0x3e16c740, v254
	v_fmamk_f32 v116, v116, 0x3e16c740, v255
	v_fmamk_f32 v85, v85, 0x3e16c740, v254
	v_fmamk_f32 v117, v117, 0x3e16c740, v255
	v_fmamk_f32 v86, v86, 0x3e16c740, v254
	v_fmamk_f32 v118, v118, 0x3e16c740, v255
	v_fmamk_f32 v87, v87, 0x3e16c740, v254
	v_fmamk_f32 v119, v119, 0x3e16c740, v255
	v_fmamk_f32 v88, v88, 0x3e16c740, v254
	v_fmamk_f32 v120, v120, 0x3e16c740, v255
	v_fmamk_f32 v89, v89, 0x3e16c740, v254
	v_fmamk_f32 v121, v121, 0x3e16c740, v255
	v_exp_f32_e32 v82, v82
	v_exp_f32_e32 v114, v114
	v_exp_f32_e32 v83, v83
	v_exp_f32_e32 v115, v115
	v_exp_f32_e32 v84, v84
	v_exp_f32_e32 v116, v116
	v_exp_f32_e32 v85, v85
	v_exp_f32_e32 v117, v117
	v_exp_f32_e32 v86, v86
	v_exp_f32_e32 v118, v118
	v_exp_f32_e32 v87, v87
	v_exp_f32_e32 v119, v119
	v_exp_f32_e32 v88, v88
	v_exp_f32_e32 v120, v120
	v_exp_f32_e32 v89, v89
	v_exp_f32_e32 v121, v121
	v_fmamk_f32 v90, v90, 0x3e16c740, v254
	v_fmamk_f32 v122, v122, 0x3e16c740, v255
	v_fmamk_f32 v91, v91, 0x3e16c740, v254
	v_fmamk_f32 v123, v123, 0x3e16c740, v255
	v_fmamk_f32 v92, v92, 0x3e16c740, v254
	v_fmamk_f32 v124, v124, 0x3e16c740, v255
	v_fmamk_f32 v93, v93, 0x3e16c740, v254
	v_fmamk_f32 v125, v125, 0x3e16c740, v255
	v_fmamk_f32 v94, v94, 0x3e16c740, v254
	v_fmamk_f32 v126, v126, 0x3e16c740, v255
	v_fmamk_f32 v95, v95, 0x3e16c740, v254
	v_fmamk_f32 v127, v127, 0x3e16c740, v255
	v_fmamk_f32 v96, v96, 0x3e16c740, v254
	v_fmamk_f32 v128, v128, 0x3e16c740, v255
	v_fmamk_f32 v97, v97, 0x3e16c740, v254
	v_fmamk_f32 v129, v129, 0x3e16c740, v255
	v_exp_f32_e32 v90, v90
	v_exp_f32_e32 v122, v122
	v_mov_b32_e32 v239, v82
	v_mov_b32_e32 v253, v114
	v_exp_f32_e32 v91, v91
	v_exp_f32_e32 v123, v123
	v_add_f32_e32 v239, v239, v83
	v_add_f32_e32 v253, v253, v115
	v_exp_f32_e32 v92, v92
	v_exp_f32_e32 v124, v124
	v_add_f32_e32 v239, v239, v84
	v_add_f32_e32 v253, v253, v116
	v_exp_f32_e32 v93, v93
	v_exp_f32_e32 v125, v125
	v_add_f32_e32 v239, v239, v85
	v_add_f32_e32 v253, v253, v117
	v_exp_f32_e32 v94, v94
	v_exp_f32_e32 v126, v126
	v_add_f32_e32 v239, v239, v86
	v_add_f32_e32 v253, v253, v118
	v_exp_f32_e32 v95, v95
	v_exp_f32_e32 v127, v127
	v_add_f32_e32 v239, v239, v87
	v_add_f32_e32 v253, v253, v119
	v_exp_f32_e32 v96, v96
	v_exp_f32_e32 v128, v128
	v_add_f32_e32 v239, v239, v88
	v_add_f32_e32 v253, v253, v120
	v_exp_f32_e32 v97, v97
	v_exp_f32_e32 v129, v129
	v_add_f32_e32 v239, v239, v89
	v_add_f32_e32 v253, v253, v121
	v_cvt_pk_bf16_f32 v82, v82, v83
	v_cvt_pk_bf16_f32 v114, v114, v115
	v_cvt_pk_bf16_f32 v83, v84, v85
	v_cvt_pk_bf16_f32 v115, v116, v117
	v_cvt_pk_bf16_f32 v84, v86, v87
	v_cvt_pk_bf16_f32 v116, v118, v119
	v_cvt_pk_bf16_f32 v85, v88, v89
	v_cvt_pk_bf16_f32 v117, v120, v121
	v_fmamk_f32 v66, v66, 0x3e16c740, v254
	v_fmamk_f32 v98, v98, 0x3e16c740, v255
	v_fmamk_f32 v67, v67, 0x3e16c740, v254
	v_fmamk_f32 v99, v99, 0x3e16c740, v255
	v_fmamk_f32 v68, v68, 0x3e16c740, v254
	v_fmamk_f32 v100, v100, 0x3e16c740, v255
	v_fmamk_f32 v69, v69, 0x3e16c740, v254
	v_fmamk_f32 v101, v101, 0x3e16c740, v255
	v_fmamk_f32 v70, v70, 0x3e16c740, v254
	v_fmamk_f32 v102, v102, 0x3e16c740, v255
	v_fmamk_f32 v71, v71, 0x3e16c740, v254
	v_fmamk_f32 v103, v103, 0x3e16c740, v255
	v_fmamk_f32 v72, v72, 0x3e16c740, v254
	v_fmamk_f32 v104, v104, 0x3e16c740, v255
	v_fmamk_f32 v73, v73, 0x3e16c740, v254
	v_fmamk_f32 v105, v105, 0x3e16c740, v255
	v_exp_f32_e32 v66, v66
	v_exp_f32_e32 v98, v98
	v_add_f32_e32 v239, v239, v90
; #define MFMA(a, b, c) __builtin_amdgcn_mfma_f32_32x32x16_bf16((a), (b), (c), 0, 0, 0)
; DI unsigned pk2(float a, float b) { f32x2 v = {a, b}; bf16x2_t r = __builtin_convertvector(v, bf16x2_t); return __builtin_bit_cast(unsigned, r); }
; template <int DQK, bool BAND, int QT> ...
;     ...
;         const float mc = -m[qt] * cc;
;         float ls = 0.f;
; #pragma unroll
;         for (int a = 0; a < 2; ++a) {
; #pragma unroll
;           for (int r = 0; r < 16; ++r) { const float pv = __builtin_amdgcn_exp2f(fmaf(s[a][qt][r], cc, mc)); s[a][qt][r] = pv; ls += pv; }
; #pragma unroll
;           for (int s2 = 0; s2 < 2; ++s2) {
;             u32x4 pk;
;             pk.x = pk2(s[a][qt][8 * s2 + 0], s[a][qt][8 * s2 + 1]);
;             pk.y = pk2(s[a][qt][8 * s2 + 2], s[a][qt][8 * s2 + 3]);
;             pk.z = pk2(s[a][qt][8 * s2 + 4], s[a][qt][8 * s2 + 5]);
;             pk.w = pk2(s[a][qt][8 * s2 + 6], s[a][qt][8 * s2 + 7]);
;             pf[qt][a * 2 + s2] = __builtin_bit_cast(bf16x8, pk);
;           }
;         }
;         l[qt] += ls;
;       }
;       __builtin_amdgcn_s_setprio(0);
;       if (more) lstore(lds + ((it + 1) & 1) * ST);
; #pragma unroll
;       for (int ks = 0; ks < 4; ++ks) {
;         const bf16x8 v0 = *(const bf16x8*)(st + v_rd + ks * 32);
;         const bf16x8 v1 = *(const bf16x8*)(st + v_rd + 32 * LROW + ks * 32);
; #pragma unroll
;         for (int qt = 0; qt < QT; ++qt) {
;           o[0][qt] = MFMA(v0, pf[qt][ks], o[0][qt]);
;           o[1][qt] = MFMA(v1, pf[qt][ks], o[1][qt]);
;         }
;       }
;     } else {
;       if (more) lstore(lds + ((it + 1) & 1) * ST);
;     }
;     __syncthreads();
;   }
	v_add_f32_e32 v253, v253, v122
	v_exp_f32_e32 v67, v67
	v_exp_f32_e32 v99, v99
	v_add_f32_e32 v239, v239, v91
	v_add_f32_e32 v253, v253, v123
	v_exp_f32_e32 v68, v68
	v_exp_f32_e32 v100, v100
	v_add_f32_e32 v239, v239, v92
	v_add_f32_e32 v253, v253, v124
	v_exp_f32_e32 v69, v69
	v_exp_f32_e32 v101, v101
	v_add_f32_e32 v239, v239, v93
	v_add_f32_e32 v253, v253, v125
	v_exp_f32_e32 v70, v70
	v_exp_f32_e32 v102, v102
	v_add_f32_e32 v239, v239, v94
	v_add_f32_e32 v253, v253, v126
	v_exp_f32_e32 v71, v71
	v_exp_f32_e32 v103, v103
	v_add_f32_e32 v239, v239, v95
	v_add_f32_e32 v253, v253, v127
	v_exp_f32_e32 v72, v72
	v_exp_f32_e32 v104, v104
	v_add_f32_e32 v239, v239, v96
	v_add_f32_e32 v253, v253, v128
	v_exp_f32_e32 v73, v73
	v_exp_f32_e32 v105, v105
	v_add_f32_e32 v239, v239, v97
	v_add_f32_e32 v253, v253, v129
	v_cvt_pk_bf16_f32 v90, v90, v91
	v_cvt_pk_bf16_f32 v122, v122, v123
	v_cvt_pk_bf16_f32 v91, v92, v93
	v_cvt_pk_bf16_f32 v123, v124, v125
	v_cvt_pk_bf16_f32 v92, v94, v95
	v_cvt_pk_bf16_f32 v124, v126, v127
	v_cvt_pk_bf16_f32 v93, v96, v97
	v_cvt_pk_bf16_f32 v125, v128, v129
	v_fmamk_f32 v74, v74, 0x3e16c740, v254
	v_fmamk_f32 v106, v106, 0x3e16c740, v255
	v_fmamk_f32 v75, v75, 0x3e16c740, v254
	v_fmamk_f32 v107, v107, 0x3e16c740, v255
	v_fmamk_f32 v76, v76, 0x3e16c740, v254
	v_fmamk_f32 v108, v108, 0x3e16c740, v255
	v_fmamk_f32 v77, v77, 0x3e16c740, v254
	v_fmamk_f32 v109, v109, 0x3e16c740, v255
	v_fmamk_f32 v78, v78, 0x3e16c740, v254
	v_fmamk_f32 v110, v110, 0x3e16c740, v255
	v_fmamk_f32 v79, v79, 0x3e16c740, v254
	v_fmamk_f32 v111, v111, 0x3e16c740, v255
	v_fmamk_f32 v80, v80, 0x3e16c740, v254
	v_fmamk_f32 v112, v112, 0x3e16c740, v255
	v_fmamk_f32 v81, v81, 0x3e16c740, v254
	v_fmamk_f32 v113, v113, 0x3e16c740, v255
	v_exp_f32_e32 v74, v74
	v_exp_f32_e32 v106, v106
	v_add_f32_e32 v239, v239, v66
	v_add_f32_e32 v253, v253, v98
	v_exp_f32_e32 v75, v75
	v_exp_f32_e32 v107, v107
	v_add_f32_e32 v239, v239, v67
	v_add_f32_e32 v253, v253, v99
	v_exp_f32_e32 v76, v76
	v_exp_f32_e32 v108, v108
	v_add_f32_e32 v239, v239, v68
	v_add_f32_e32 v253, v253, v100
	v_exp_f32_e32 v77, v77
	v_exp_f32_e32 v109, v109
	v_add_f32_e32 v239, v239, v69
	v_add_f32_e32 v253, v253, v101
	v_exp_f32_e32 v78, v78
	v_exp_f32_e32 v110, v110
	v_add_f32_e32 v239, v239, v70
	v_add_f32_e32 v253, v253, v102
	v_exp_f32_e32 v79, v79
	v_exp_f32_e32 v111, v111
	v_add_f32_e32 v239, v239, v71
	v_add_f32_e32 v253, v253, v103
	v_exp_f32_e32 v80, v80
	v_exp_f32_e32 v112, v112
	v_add_f32_e32 v239, v239, v72
	v_add_f32_e32 v253, v253, v104
	v_exp_f32_e32 v81, v81
	v_exp_f32_e32 v113, v113
	v_add_f32_e32 v239, v239, v73
	v_add_f32_e32 v253, v253, v105
	v_cvt_pk_bf16_f32 v66, v66, v67
	v_cvt_pk_bf16_f32 v98, v98, v99
	v_cvt_pk_bf16_f32 v67, v68, v69
	v_cvt_pk_bf16_f32 v99, v100, v101
	v_cvt_pk_bf16_f32 v68, v70, v71
	v_cvt_pk_bf16_f32 v100, v102, v103
	v_cvt_pk_bf16_f32 v69, v72, v73
	v_cvt_pk_bf16_f32 v101, v104, v105
	v_add_f32_e32 v239, v239, v74
	v_add_f32_e32 v253, v253, v106
	v_add_f32_e32 v239, v239, v75
	v_add_f32_e32 v253, v253, v107
	v_add_f32_e32 v239, v239, v76
	v_add_f32_e32 v253, v253, v108
	v_add_f32_e32 v239, v239, v77
	v_add_f32_e32 v253, v253, v109
	v_add_f32_e32 v239, v239, v78
	v_add_f32_e32 v253, v253, v110
	v_add_f32_e32 v239, v239, v79
	v_add_f32_e32 v253, v253, v111
	v_add_f32_e32 v239, v239, v80
	v_add_f32_e32 v253, v253, v112
	v_add_f32_e32 v239, v239, v81
	v_add_f32_e32 v253, v253, v113
	v_cvt_pk_bf16_f32 v74, v74, v75
	v_cvt_pk_bf16_f32 v106, v106, v107
	v_cvt_pk_bf16_f32 v75, v76, v77
	v_cvt_pk_bf16_f32 v107, v108, v109
	v_cvt_pk_bf16_f32 v76, v78, v79
	v_cvt_pk_bf16_f32 v108, v110, v111
	v_cvt_pk_bf16_f32 v77, v80, v81
	v_cvt_pk_bf16_f32 v109, v112, v113
	v_add_f32_e32 v236, v236, v239
	v_add_f32_e32 v207, v207, v253
	ds_read_b128 v[86:89], v234 offset:13312
	ds_read_b128 v[94:97], v234 offset:17920
	ds_read_b128 v[70:73], v234 offset:13344
	ds_read_b128 v[78:81], v234 offset:17952
	ds_read_b128 v[118:121], v234 offset:13376
	ds_read_b128 v[126:129], v234 offset:17984
	ds_read_b128 v[102:105], v234 offset:13408
	ds_read_b128 v[110:113], v234 offset:18016
	s_waitcnt lgkmcnt(7)
	v_mfma_f32_32x32x16_bf16 v[50:65], v[86:89], v[82:85], v[50:65]
	v_mfma_f32_32x32x16_bf16 v[18:33], v[86:89], v[114:117], v[18:33]
	s_waitcnt lgkmcnt(6)
	v_mfma_f32_32x32x16_bf16 v[34:49], v[94:97], v[82:85], v[34:49]
	v_mfma_f32_32x32x16_bf16 v[2:17], v[94:97], v[114:117], v[2:17]
	v_lshl_add_u64 v[208:209], v[208:209], 0, s[76:77]
	v_lshl_add_u64 v[210:211], v[210:211], 0, s[76:77]
	v_lshl_add_u64 v[212:213], v[212:213], 0, s[84:85]
	v_lshl_add_u64 v[214:215], v[214:215], 0, s[84:85]
	v_lshl_add_u64 v[216:217], v[216:217], 0, s[84:85]
	s_waitcnt lgkmcnt(5)
	v_mfma_f32_32x32x16_bf16 v[50:65], v[70:73], v[90:93], v[50:65]
	v_mfma_f32_32x32x16_bf16 v[18:33], v[70:73], v[122:125], v[18:33]
	s_waitcnt lgkmcnt(4)
	v_mfma_f32_32x32x16_bf16 v[34:49], v[78:81], v[90:93], v[34:49]
	v_mfma_f32_32x32x16_bf16 v[2:17], v[78:81], v[122:125], v[2:17]
	s_waitcnt lgkmcnt(3)
	v_mfma_f32_32x32x16_bf16 v[50:65], v[118:121], v[66:69], v[50:65]
	v_mfma_f32_32x32x16_bf16 v[18:33], v[118:121], v[98:101], v[18:33]
	s_waitcnt lgkmcnt(2)
	v_mfma_f32_32x32x16_bf16 v[34:49], v[126:129], v[66:69], v[34:49]
	v_mfma_f32_32x32x16_bf16 v[2:17], v[126:129], v[98:101], v[2:17]
	s_bitcmp1_b32 s1, 0
	s_cselect_b32 s7, -1, 1
	s_mulk_i32 s7, 0x5800
	v_add_u32_e32 v235, s7, v235
	v_add_u32_e32 v234, s7, v234
	s_add_i32 s1, s1, 1
	s_add_i32 s6, s6, 64
	s_waitcnt lgkmcnt(0)
	s_barrier
	v_mfma_f32_32x32x16_bf16 v[50:65], v[102:105], v[74:77], v[50:65]
	v_mfma_f32_32x32x16_bf16 v[18:33], v[102:105], v[106:109], v[18:33]
	v_mfma_f32_32x32x16_bf16 v[34:49], v[110:113], v[74:77], v[34:49]
	v_mfma_f32_32x32x16_bf16 v[2:17], v[110:113], v[106:109], v[2:17]
	s_cmp_lg_u32 s21, s1
	s_cbranch_scc1 .Lmla_top
	s_branch .LBB0_663

; #define LAS __attribute__((address_space(3)))
; __global__ void __launch_bounds__(NTHREADS, 2) mega_kernel(Params p) {
;   extern __shared__ __attribute__((aligned(16))) char lds[];
;   cg::grid_group grid = cg::this_grid();
;   volatile LAS unsigned* xst = (volatile LAS unsigned*)(lds + OFF_RR + 512);
;   if (threadIdx.x == 0) { xst[0] = 0u; xst[1] = 0u; }
;   __syncthreads();
;   const XcdBarrier xb = xcd_barrier_post((unsigned*)(p.ws + OFF_BAR), xst);
	.amdhsa_kernel _Z11mega_kernel6Params
		.amdhsa_group_segment_fixed_size 0
		.amdhsa_private_segment_fixed_size 0
		.amdhsa_kernarg_size 528
		.amdhsa_user_sgpr_count 2
		.amdhsa_user_sgpr_dispatch_ptr 0
		.amdhsa_user_sgpr_queue_ptr 0
		.amdhsa_user_sgpr_kernarg_segment_ptr 1
		.amdhsa_user_sgpr_dispatch_id 0
		.amdhsa_user_sgpr_kernarg_preload_length 0
		.amdhsa_user_sgpr_kernarg_preload_offset 0
		.amdhsa_user_sgpr_private_segment_size 0
		.amdhsa_uses_dynamic_stack 0
		.amdhsa_enable_private_segment 0
		.amdhsa_system_sgpr_workgroup_id_x 1
		.amdhsa_system_sgpr_workgroup_id_y 0
		.amdhsa_system_sgpr_workgroup_id_z 0
		.amdhsa_system_sgpr_workgroup_info 0
		.amdhsa_system_vgpr_workitem_id 2
		.amdhsa_next_free_vgpr 256
		.amdhsa_next_free_sgpr 100
		.amdhsa_accum_offset 256
		.amdhsa_reserve_vcc 1
		.amdhsa_float_round_mode_32 0
		.amdhsa_float_round_mode_16_64 0
		.amdhsa_float_denorm_mode_32 3
		.amdhsa_float_denorm_mode_16_64 3
		.amdhsa_dx10_clamp 1
		.amdhsa_ieee_mode 1
		.amdhsa_fp16_overflow 0
		.amdhsa_tg_split 0
		.amdhsa_exception_fp_ieee_invalid_op 0
		.amdhsa_exception_fp_denorm_src 0
		.amdhsa_exception_fp_ieee_div_zero 0
		.amdhsa_exception_fp_ieee_overflow 0
		.amdhsa_exception_fp_ieee_underflow 0
		.amdhsa_exception_fp_ieee_inexact 0
		.amdhsa_exception_int_div_zero 0
	.end_amdhsa_kernel

; __global__ void __launch_bounds__(NTHREADS, 2) mega_kernel(Params p) {
;   extern __shared__ __attribute__((aligned(16))) char lds[];
amdhsa.kernels:
  - .agpr_count:     0
    .args:
      - .offset:         0
        .size:           272
        .value_kind:     by_value
      - .offset:         272
        .size:           4
        .value_kind:     hidden_block_count_x
      - .offset:         276
        .size:           4
        .value_kind:     hidden_block_count_y
      - .offset:         280
        .size:           4
        .value_kind:     hidden_block_count_z
      - .offset:         284
        .size:           2
        .value_kind:     hidden_group_size_x
      - .offset:         286
        .size:           2
        .value_kind:     hidden_group_size_y
      - .offset:         288
        .size:           2
        .value_kind:     hidden_group_size_z
      - .offset:         290
        .size:           2
        .value_kind:     hidden_remainder_x
      - .offset:         292
        .size:           2
        .value_kind:     hidden_remainder_y
      - .offset:         294
        .size:           2
        .value_kind:     hidden_remainder_z
      - .offset:         312
        .size:           8
        .value_kind:     hidden_global_offset_x
      - .offset:         320
        .size:           8
        .value_kind:     hidden_global_offset_y
      - .offset:         328
        .size:           8
        .value_kind:     hidden_global_offset_z
      - .offset:         336
        .size:           2
        .value_kind:     hidden_grid_dims
      - .offset:         360
        .size:           8
        .value_kind:     hidden_multigrid_sync_arg
      - .offset:         392
        .size:           4
        .value_kind:     hidden_dynamic_lds_size
    .group_segment_fixed_size: 0
    .kernarg_segment_align: 8
    .kernarg_segment_size: 528
    .language:       OpenCL C
    .language_version:
      - 2
      - 0
    .max_flat_workgroup_size: 256
    .name:           _Z11mega_kernel6Params
    .private_segment_fixed_size: 0
    .sgpr_count:     106
    .sgpr_spill_count: 285
    .symbol:         _Z11mega_kernel6Params.kd
    .uniform_work_group_size: 1
    .uses_dynamic_stack: false
    .vgpr_count:     256
    .vgpr_spill_count: 0
    .wavefront_size: 64
